# gla_seq output part: the four state-fragment ds_reads issued together (own registers, counted lgkmcnt 3..0) instead of read/wait/MFMA x4
# speedup vs baseline: 1.0055x; 1.0036x over previous
; __device__ __forceinline__ f32x4 mma_gl(const bf16x8* af, const bfr* B, int ldb, int ksteps, f32x4 acc, int fr, int fq) {
;   bf16x8 b0 = *(const bf16x8*)(B + fr * ldb + 0 * 32 + fq * 8);
;   bf16x8 b1 = *(const bf16x8*)(B + fr * ldb + 1 * 32 + fq * 8);
;   bf16x8 b2 = *(const bf16x8*)(B + fr * ldb + 2 * 32 + fq * 8);
;   bf16x8 b3 = *(const bf16x8*)(B + fr * ldb + 3 * 32 + fq * 8);
;   f32x4 c0 = acc, c1 = f32x4{0.f, 0.f, 0.f, 0.f};
;   c0 = __builtin_amdgcn_mfma_f32_16x16x32_bf16(af[0], b0, c0, 0, 0, 0);
;   c1 = __builtin_amdgcn_mfma_f32_16x16x32_bf16(af[1], b1, c1, 0, 0, 0);
;   c0 = __builtin_amdgcn_mfma_f32_16x16x32_bf16(af[2], b2, c0, 0, 0, 0);
;   c1 = __builtin_amdgcn_mfma_f32_16x16x32_bf16(af[3], b3, c1, 0, 0, 0);
;   (void)ksteps;
;   return c0 + c1;
; }
.LBB0_353:
	ds_read_b128 v[198:201], v195
	ds_read_b128 v[202:205], v195 offset:64
	ds_read_b128 v[206:209], v195 offset:128
	ds_read_b128 v[210:213], v195 offset:192
	s_add_i32 s60, s72, s57
	s_ashr_i32 s61, s60, 31
	v_cmp_gt_u32_e32 vcc, s86, v197
	s_lshl_b64 s[60:61], s[60:61], 11
	s_waitcnt vmcnt(59) lgkmcnt(3)
	v_mfma_f32_16x16x32_bf16 v[134:137], v[134:137], v[198:201], 0
	s_waitcnt vmcnt(58) lgkmcnt(2)
	v_mfma_f32_16x16x32_bf16 v[130:133], v[130:133], v[202:205], 0
	s_waitcnt vmcnt(57) lgkmcnt(1)
	v_mfma_f32_16x16x32_bf16 v[126:129], v[126:129], v[206:209], v[134:137]
	s_waitcnt vmcnt(56) lgkmcnt(0)
	v_mfma_f32_16x16x32_bf16 v[122:125], v[122:125], v[210:213], v[130:133]
	s_nop 7
	v_pk_add_f32 v[124:125], v[128:129], v[124:125]
	v_pk_add_f32 v[122:123], v[126:127], v[122:123]
	s_waitcnt vmcnt(55)
	v_lshlrev_b32_e32 v128, 16, v193
	v_add_f32_e32 v122, v122, v128
	v_cvt_pk_bf16_f32 v122, v122, s0
	v_cndmask_b32_sdwa v122, v1, v122, vcc dst_sel:DWORD dst_unused:UNUSED_PAD src0_sel:DWORD src1_sel:WORD_0
	v_lshl_add_u64 v[126:127], v[148:149], 0, s[60:61]
	global_store_short v[126:127], v122, off
	s_waitcnt vmcnt(55)
	v_lshlrev_b32_e32 v122, 16, v192
	v_add_f32_e32 v128, v123, v122
	v_add_u32_e32 v122, 1, v197
	s_mov_b64 s[60:61], 0x800
	v_cmp_gt_u32_e32 vcc, s86, v122
	v_lshl_add_u64 v[122:123], v[126:127], 0, s[60:61]
	v_cvt_pk_bf16_f32 v128, v128, s0
	v_cndmask_b32_sdwa v128, v1, v128, vcc dst_sel:DWORD dst_unused:UNUSED_PAD src0_sel:DWORD src1_sel:WORD_0
	global_store_short v[122:123], v128, off
	s_waitcnt vmcnt(55)
	v_lshlrev_b32_e32 v122, 16, v191
	v_add_f32_e32 v124, v124, v122
	v_add_u32_e32 v122, 2, v197
	s_mov_b64 s[60:61], 0x1000
	v_cmp_gt_u32_e32 vcc, s86, v122
	v_lshl_add_u64 v[122:123], v[126:127], 0, s[60:61]
	v_cvt_pk_bf16_f32 v124, v124, s0
	v_cndmask_b32_sdwa v124, v1, v124, vcc dst_sel:DWORD dst_unused:UNUSED_PAD src0_sel:DWORD src1_sel:WORD_0
	global_store_short v[122:123], v124, off
	s_waitcnt vmcnt(55)
	v_lshlrev_b32_e32 v122, 16, v190
	v_add_f32_e32 v124, v125, v122
	v_add_u32_e32 v122, 3, v197
	v_cmp_gt_u32_e32 vcc, s86, v122
	s_mov_b64 s[60:61], 0x1800
	v_cvt_pk_bf16_f32 v124, v124, s0
	v_lshl_add_u64 v[122:123], v[126:127], 0, s[60:61]
	v_cndmask_b32_sdwa v124, v1, v124, vcc dst_sel:DWORD dst_unused:UNUSED_PAD src0_sel:DWORD src1_sel:WORD_0
	global_store_short v[122:123], v124, off
.LBB0_354:
	s_or_b64 exec, exec, s[76:77]
	s_add_i32 s56, s58, -3
	s_min_i32 s59, s56, s3
	s_lshl_b32 s60, s59, 5
	s_add_i32 s60, s60, s72
	s_ashr_i32 s61, s60, 31
	s_mul_i32 s62, s60, 0x1c00
	s_mul_hi_i32 s63, s60, 0x1c00
	s_add_u32 s62, s36, s62
	s_waitcnt vmcnt(52)
	v_pk_mul_f32 v[12:13], v[104:105], v[12:13]
	v_pk_mul_f32 v[10:11], v[102:103], v[10:11]
	v_pk_mul_f32 v[24:25], v[104:105], v[24:25]
	v_pk_mul_f32 v[22:23], v[102:103], v[22:23]
	s_addc_u32 s63, s37, s63
	v_mfma_f32_16x16x32_bf16 v[10:13], v[90:93], v[106:109], v[10:13]
	s_lshl_b64 s[60:61], s[60:61], 11
	s_add_i32 s64, s59, s74
	s_ashr_i32 s65, s64, 31
	v_mfma_f32_16x16x32_bf16 v[22:25], v[90:93], v[94:97], v[22:25]
	v_lshl_add_u64 v[90:91], s[62:63], 0, v[150:151]
	global_load_dwordx4 v[134:137], v[90:91], off
	global_load_dwordx4 v[130:133], v[90:91], off offset:64
	global_load_dwordx4 v[126:129], v[90:91], off offset:128
	global_load_dwordx4 v[122:125], v[90:91], off offset:192
	v_lshl_add_u64 v[90:91], v[148:149], 0, s[60:61]
	v_add_co_u32_e32 v92, vcc, s75, v90
	v_lshl_add_u64 v[94:95], s[62:63], 0, v[0:1]
	s_nop 0
	v_addc_co_u32_e32 v93, vcc, 0, v91, vcc
	global_load_ushort v193, v[90:91], off
	global_load_ushort v192, v[90:91], off offset:2048
	global_load_ushort v191, v[92:93], off
	global_load_ushort v190, v[92:93], off offset:2048
	v_lshl_add_u64 v[90:91], s[62:63], 0, v[152:153]
	global_load_dwordx4 v[90:93], v[90:91], off
	s_nop 0
	global_load_dwordx4 v[106:109], v[94:95], off
	v_add_co_u32_e32 v94, vcc, 0x7000, v94
	s_lshl_b64 s[60:61], s[64:65], 11
	s_nop 0
	v_addc_co_u32_e32 v95, vcc, 0, v95, vcc
	v_lshl_add_u64 v[102:103], v[154:155], 0, s[60:61]
	global_load_dwordx4 v[94:97], v[94:95], off
	v_cvt_pk_bf16_f32 v167, v12, v13
	global_load_dwordx4 v[102:105], v[102:103], off
	v_cvt_pk_bf16_f32 v166, v10, v11
	ds_write_b64 v196, v[166:167] offset:8704
	v_cvt_pk_bf16_f32 v167, v24, v25
	v_cvt_pk_bf16_f32 v166, v22, v23
	ds_write_b64 v196, v[166:167] offset:13056
	s_waitcnt lgkmcnt(0)
	s_barrier
	s_and_saveexec_b64 s[76:77], s[38:39]
	s_cbranch_execz .Lgla_dummy_a
	ds_read_b128 v[198:201], v195 offset:8704
	ds_read_b128 v[202:205], v195 offset:8768
	ds_read_b128 v[206:209], v195 offset:8832
	ds_read_b128 v[210:213], v195 offset:8896
	s_add_i32 s59, s72, s57
	s_add_i32 s60, s59, 32
	s_ashr_i32 s61, s60, 31
	s_lshl_b64 s[60:61], s[60:61], 11
	s_waitcnt vmcnt(59) lgkmcnt(3)
	v_mfma_f32_16x16x32_bf16 v[118:121], v[118:121], v[198:201], 0
	s_waitcnt vmcnt(58) lgkmcnt(2)
	v_mfma_f32_16x16x32_bf16 v[114:117], v[114:117], v[202:205], 0
	s_waitcnt vmcnt(57) lgkmcnt(1)
	v_mfma_f32_16x16x32_bf16 v[110:113], v[110:113], v[206:209], v[118:121]
	s_waitcnt vmcnt(56) lgkmcnt(0)
	v_mfma_f32_16x16x32_bf16 v[98:101], v[98:101], v[210:213], v[114:117]
	s_nop 7
	v_pk_add_f32 v[100:101], v[112:113], v[100:101]
	v_pk_add_f32 v[98:99], v[110:111], v[98:99]
	s_waitcnt vmcnt(55)
	v_lshlrev_b32_e32 v113, 16, v189
	v_add_u32_e32 v112, 32, v197
	v_add_f32_e32 v98, v98, v113
	v_cmp_gt_u32_e32 vcc, s86, v112
	v_cvt_pk_bf16_f32 v98, v98, s0
	v_lshl_add_u64 v[110:111], v[148:149], 0, s[60:61]
	v_cndmask_b32_sdwa v98, v1, v98, vcc dst_sel:DWORD dst_unused:UNUSED_PAD src0_sel:DWORD src1_sel:WORD_0
	global_store_short v[110:111], v98, off
	s_waitcnt vmcnt(55)
	v_lshlrev_b32_e32 v98, 16, v187
	v_add_f32_e32 v112, v99, v98
	v_add_u32_e32 v98, 33, v197
	s_mov_b64 s[60:61], 0x800
	v_cmp_gt_u32_e32 vcc, s86, v98
	v_lshl_add_u64 v[98:99], v[110:111], 0, s[60:61]
	v_cvt_pk_bf16_f32 v112, v112, s0
	v_cndmask_b32_sdwa v112, v1, v112, vcc dst_sel:DWORD dst_unused:UNUSED_PAD src0_sel:DWORD src1_sel:WORD_0
	global_store_short v[98:99], v112, off
	s_waitcnt vmcnt(55)
	v_lshlrev_b32_e32 v98, 16, v188
	v_add_f32_e32 v100, v100, v98
	v_add_u32_e32 v98, 34, v197
	s_mov_b64 s[60:61], 0x1000
	v_cmp_gt_u32_e32 vcc, s86, v98
	v_lshl_add_u64 v[98:99], v[110:111], 0, s[60:61]
	v_cvt_pk_bf16_f32 v100, v100, s0
	v_cndmask_b32_sdwa v100, v1, v100, vcc dst_sel:DWORD dst_unused:UNUSED_PAD src0_sel:DWORD src1_sel:WORD_0
	global_store_short v[98:99], v100, off
	s_waitcnt vmcnt(55)
	v_lshlrev_b32_e32 v98, 16, v186
	v_add_f32_e32 v100, v101, v98
	v_add_u32_e32 v98, 35, v197
	v_cmp_gt_u32_e32 vcc, s86, v98
	s_mov_b64 s[60:61], 0x1800
	v_cvt_pk_bf16_f32 v100, v100, s0
	v_lshl_add_u64 v[98:99], v[110:111], 0, s[60:61]
	v_cndmask_b32_sdwa v100, v1, v100, vcc dst_sel:DWORD dst_unused:UNUSED_PAD src0_sel:DWORD src1_sel:WORD_0
	global_store_short v[98:99], v100, off
	s_branch .LBB0_356

; __device__ void gla_seq(const KP& p, int l, int s, int h, int vq) {
;     ...
;       GLA_LOAD(k, min(st + 4, nst - 1));
.LBB0_356:
	s_or_b64 exec, exec, s[76:77]
	s_add_i32 s59, s58, -2
	s_min_i32 s59, s59, s3
	s_lshl_b32 s60, s59, 5
	s_add_i32 s60, s60, s72
	s_ashr_i32 s61, s60, 31
	s_mul_i32 s62, s60, 0x1c00
	s_mul_hi_i32 s63, s60, 0x1c00
	s_add_u32 s62, s36, s62
	s_waitcnt vmcnt(52)
	v_pk_mul_f32 v[12:13], v[68:69], v[12:13]
	v_pk_mul_f32 v[10:11], v[66:67], v[10:11]
	v_pk_mul_f32 v[24:25], v[68:69], v[24:25]
	v_pk_mul_f32 v[22:23], v[66:67], v[22:23]
	s_addc_u32 s63, s37, s63
	v_mfma_f32_16x16x32_bf16 v[10:13], v[58:61], v[74:77], v[10:13]
	s_lshl_b64 s[60:61], s[60:61], 11
	s_add_i32 s64, s59, s74
	s_ashr_i32 s65, s64, 31
	v_mfma_f32_16x16x32_bf16 v[22:25], v[58:61], v[62:65], v[22:25]
	v_lshl_add_u64 v[58:59], s[62:63], 0, v[150:151]
	global_load_dwordx4 v[118:121], v[58:59], off
	global_load_dwordx4 v[114:117], v[58:59], off offset:64
	global_load_dwordx4 v[110:113], v[58:59], off offset:128
	global_load_dwordx4 v[98:101], v[58:59], off offset:192
	v_lshl_add_u64 v[58:59], v[148:149], 0, s[60:61]
	v_add_co_u32_e32 v60, vcc, s75, v58
	v_lshl_add_u64 v[62:63], s[62:63], 0, v[0:1]
	s_nop 0
	v_addc_co_u32_e32 v61, vcc, 0, v59, vcc
	global_load_ushort v189, v[58:59], off
	global_load_ushort v187, v[58:59], off offset:2048
	global_load_ushort v188, v[60:61], off
	global_load_ushort v186, v[60:61], off offset:2048
	v_lshl_add_u64 v[58:59], s[62:63], 0, v[152:153]
	global_load_dwordx4 v[58:61], v[58:59], off
	s_nop 0
	global_load_dwordx4 v[74:77], v[62:63], off
	v_add_co_u32_e32 v62, vcc, 0x7000, v62
	s_lshl_b64 s[60:61], s[64:65], 11
	s_nop 0
	v_addc_co_u32_e32 v63, vcc, 0, v63, vcc
	v_lshl_add_u64 v[66:67], v[154:155], 0, s[60:61]
	global_load_dwordx4 v[62:65], v[62:63], off
	v_cvt_pk_bf16_f32 v167, v12, v13
	global_load_dwordx4 v[66:69], v[66:67], off
	v_cvt_pk_bf16_f32 v166, v10, v11
	ds_write_b64 v196, v[166:167]
	v_cvt_pk_bf16_f32 v167, v24, v25
	v_cvt_pk_bf16_f32 v166, v22, v23
	ds_write_b64 v196, v[166:167] offset:4352
	s_waitcnt lgkmcnt(0)
	s_barrier
	s_and_saveexec_b64 s[76:77], s[38:39]
	s_cbranch_execz .Lgla_dummy_b
	ds_read_b128 v[198:201], v195
	ds_read_b128 v[202:205], v195 offset:64
	ds_read_b128 v[206:209], v195 offset:128
	ds_read_b128 v[210:213], v195 offset:192
	s_add_i32 s59, s72, s57
	s_add_i32 s60, s59, 64
	s_ashr_i32 s61, s60, 31
	s_lshl_b64 s[60:61], s[60:61], 11
	s_waitcnt vmcnt(59) lgkmcnt(3)
	v_mfma_f32_16x16x32_bf16 v[86:89], v[86:89], v[198:201], 0
	s_waitcnt vmcnt(58) lgkmcnt(2)
	v_mfma_f32_16x16x32_bf16 v[82:85], v[82:85], v[202:205], 0
	s_waitcnt vmcnt(57) lgkmcnt(1)
	v_mfma_f32_16x16x32_bf16 v[78:81], v[78:81], v[206:209], v[86:89]
	s_waitcnt vmcnt(56) lgkmcnt(0)
	v_mfma_f32_16x16x32_bf16 v[70:73], v[70:73], v[210:213], v[82:85]
	s_nop 7
	v_pk_add_f32 v[72:73], v[80:81], v[72:73]
	v_pk_add_f32 v[70:71], v[78:79], v[70:71]
	s_waitcnt vmcnt(55)
	v_lshlrev_b32_e32 v81, 16, v185
	v_add_u32_e32 v80, 64, v197
	v_add_f32_e32 v70, v70, v81
	v_cmp_gt_u32_e32 vcc, s86, v80
	v_cvt_pk_bf16_f32 v70, v70, s0
	v_lshl_add_u64 v[78:79], v[148:149], 0, s[60:61]
	v_cndmask_b32_sdwa v70, v1, v70, vcc dst_sel:DWORD dst_unused:UNUSED_PAD src0_sel:DWORD src1_sel:WORD_0
	global_store_short v[78:79], v70, off
	s_waitcnt vmcnt(55)
	v_lshlrev_b32_e32 v70, 16, v183
	v_add_f32_e32 v80, v71, v70
	v_add_u32_e32 v70, 0x41, v197
	s_mov_b64 s[60:61], 0x800
	v_cmp_gt_u32_e32 vcc, s86, v70
	v_lshl_add_u64 v[70:71], v[78:79], 0, s[60:61]
	v_cvt_pk_bf16_f32 v80, v80, s0
	v_cndmask_b32_sdwa v80, v1, v80, vcc dst_sel:DWORD dst_unused:UNUSED_PAD src0_sel:DWORD src1_sel:WORD_0
	global_store_short v[70:71], v80, off
	s_waitcnt vmcnt(55)
	v_lshlrev_b32_e32 v70, 16, v184
	v_add_f32_e32 v72, v72, v70
	v_add_u32_e32 v70, 0x42, v197
	s_mov_b64 s[60:61], 0x1000
	v_cmp_gt_u32_e32 vcc, s86, v70
	v_lshl_add_u64 v[70:71], v[78:79], 0, s[60:61]
	v_cvt_pk_bf16_f32 v72, v72, s0
	v_cndmask_b32_sdwa v72, v1, v72, vcc dst_sel:DWORD dst_unused:UNUSED_PAD src0_sel:DWORD src1_sel:WORD_0
	global_store_short v[70:71], v72, off
	s_waitcnt vmcnt(55)
	v_lshlrev_b32_e32 v70, 16, v182
	v_add_f32_e32 v72, v73, v70
	v_add_u32_e32 v70, 0x43, v197
	v_cmp_gt_u32_e32 vcc, s86, v70
	s_mov_b64 s[60:61], 0x1800
	v_cvt_pk_bf16_f32 v72, v72, s0
	v_lshl_add_u64 v[70:71], v[78:79], 0, s[60:61]
	v_cndmask_b32_sdwa v72, v1, v72, vcc dst_sel:DWORD dst_unused:UNUSED_PAD src0_sel:DWORD src1_sel:WORD_0
	global_store_short v[70:71], v72, off
	s_branch .LBB0_358

; __device__ void gla_seq(const KP& p, int l, int s, int h, int vq) {
;     ...
;       GLA_LOAD(k, min(st + 4, nst - 1));
.LBB0_358:
	s_or_b64 exec, exec, s[76:77]
	s_add_i32 s59, s58, -1
	s_min_i32 s59, s59, s3
	s_lshl_b32 s60, s59, 5
	s_add_i32 s60, s60, s72
	s_ashr_i32 s61, s60, 31
	s_mul_i32 s62, s60, 0x1c00
	s_mul_hi_i32 s63, s60, 0x1c00
	s_add_u32 s62, s36, s62
	s_waitcnt vmcnt(52)
	v_pk_mul_f32 v[12:13], v[52:53], v[12:13]
	v_pk_mul_f32 v[10:11], v[50:51], v[10:11]
	v_pk_mul_f32 v[24:25], v[52:53], v[24:25]
	v_pk_mul_f32 v[22:23], v[50:51], v[22:23]
	s_addc_u32 s63, s37, s63
	v_mfma_f32_16x16x32_bf16 v[10:13], v[30:33], v[54:57], v[10:13]
	s_lshl_b64 s[60:61], s[60:61], 11
	s_add_i32 s64, s59, s74
	s_ashr_i32 s65, s64, 31
	v_mfma_f32_16x16x32_bf16 v[22:25], v[30:33], v[42:45], v[22:25]
	v_lshl_add_u64 v[30:31], s[62:63], 0, v[150:151]
	global_load_dwordx4 v[86:89], v[30:31], off
	global_load_dwordx4 v[82:85], v[30:31], off offset:64
	global_load_dwordx4 v[78:81], v[30:31], off offset:128
	global_load_dwordx4 v[70:73], v[30:31], off offset:192
	v_lshl_add_u64 v[30:31], v[148:149], 0, s[60:61]
	v_add_co_u32_e32 v32, vcc, s75, v30
	v_lshl_add_u64 v[42:43], s[62:63], 0, v[0:1]
	s_nop 0
	v_addc_co_u32_e32 v33, vcc, 0, v31, vcc
	global_load_ushort v185, v[30:31], off
	global_load_ushort v183, v[30:31], off offset:2048
	global_load_ushort v184, v[32:33], off
	global_load_ushort v182, v[32:33], off offset:2048
	v_lshl_add_u64 v[30:31], s[62:63], 0, v[152:153]
	global_load_dwordx4 v[30:33], v[30:31], off
	s_nop 0
	global_load_dwordx4 v[54:57], v[42:43], off
	v_add_co_u32_e32 v42, vcc, 0x7000, v42
	s_lshl_b64 s[60:61], s[64:65], 11
	s_nop 0
	v_addc_co_u32_e32 v43, vcc, 0, v43, vcc
	v_lshl_add_u64 v[50:51], v[154:155], 0, s[60:61]
	global_load_dwordx4 v[42:45], v[42:43], off
	v_cvt_pk_bf16_f32 v167, v12, v13
	global_load_dwordx4 v[50:53], v[50:51], off
	v_cvt_pk_bf16_f32 v166, v10, v11
	ds_write_b64 v196, v[166:167] offset:8704
	v_cvt_pk_bf16_f32 v167, v24, v25
	v_cvt_pk_bf16_f32 v166, v22, v23
	ds_write_b64 v196, v[166:167] offset:13056
	s_waitcnt lgkmcnt(0)
	s_barrier
	s_and_saveexec_b64 s[76:77], s[38:39]
	s_cbranch_execz .Lgla_dummy_c
	ds_read_b128 v[198:201], v195 offset:8704
	ds_read_b128 v[202:205], v195 offset:8768
	ds_read_b128 v[206:209], v195 offset:8832
	ds_read_b128 v[210:213], v195 offset:8896
	s_add_i32 s59, s72, s57
	s_add_i32 s60, s59, 0x60
	s_ashr_i32 s61, s60, 31
	s_lshl_b64 s[60:61], s[60:61], 11
	s_waitcnt vmcnt(59) lgkmcnt(3)
	v_mfma_f32_16x16x32_bf16 v[46:49], v[46:49], v[198:201], 0
	s_waitcnt vmcnt(58) lgkmcnt(2)
	v_mfma_f32_16x16x32_bf16 v[38:41], v[38:41], v[202:205], 0
	s_waitcnt vmcnt(57) lgkmcnt(1)
	v_mfma_f32_16x16x32_bf16 v[34:37], v[34:37], v[206:209], v[46:49]
	s_waitcnt vmcnt(56) lgkmcnt(0)
	v_mfma_f32_16x16x32_bf16 v[26:29], v[26:29], v[210:213], v[38:41]
	s_nop 7
	v_pk_add_f32 v[28:29], v[36:37], v[28:29]
	v_pk_add_f32 v[26:27], v[34:35], v[26:27]
	s_waitcnt vmcnt(55)
	v_lshlrev_b32_e32 v37, 16, v180
	v_add_u32_e32 v36, 0x60, v197
	v_add_f32_e32 v26, v26, v37
	v_cmp_gt_u32_e32 vcc, s86, v36
	v_cvt_pk_bf16_f32 v26, v26, s0
	v_lshl_add_u64 v[34:35], v[148:149], 0, s[60:61]
	v_cndmask_b32_sdwa v26, v1, v26, vcc dst_sel:DWORD dst_unused:UNUSED_PAD src0_sel:DWORD src1_sel:WORD_0
	global_store_short v[34:35], v26, off
	s_waitcnt vmcnt(55)
	v_lshlrev_b32_e32 v26, 16, v178
	v_add_f32_e32 v36, v27, v26
	v_add_u32_e32 v26, 0x61, v197
	s_mov_b64 s[60:61], 0x800
	v_cmp_gt_u32_e32 vcc, s86, v26
	v_lshl_add_u64 v[26:27], v[34:35], 0, s[60:61]
	v_cvt_pk_bf16_f32 v36, v36, s0
	v_cndmask_b32_sdwa v36, v1, v36, vcc dst_sel:DWORD dst_unused:UNUSED_PAD src0_sel:DWORD src1_sel:WORD_0
	global_store_short v[26:27], v36, off
	s_waitcnt vmcnt(55)
	v_lshlrev_b32_e32 v26, 16, v179
	v_add_f32_e32 v28, v28, v26
	v_add_u32_e32 v26, 0x62, v197
	s_mov_b64 s[60:61], 0x1000
	v_cmp_gt_u32_e32 vcc, s86, v26
	v_lshl_add_u64 v[26:27], v[34:35], 0, s[60:61]
	v_cvt_pk_bf16_f32 v28, v28, s0
	v_cndmask_b32_sdwa v28, v1, v28, vcc dst_sel:DWORD dst_unused:UNUSED_PAD src0_sel:DWORD src1_sel:WORD_0
	global_store_short v[26:27], v28, off
	s_waitcnt vmcnt(55)
	v_lshlrev_b32_e32 v26, 16, v176
	v_add_f32_e32 v28, v29, v26
	v_add_u32_e32 v26, 0x63, v197
	v_cmp_gt_u32_e32 vcc, s86, v26
	s_mov_b64 s[60:61], 0x1800
	v_cvt_pk_bf16_f32 v28, v28, s0
	v_lshl_add_u64 v[26:27], v[34:35], 0, s[60:61]
	v_cndmask_b32_sdwa v28, v1, v28, vcc dst_sel:DWORD dst_unused:UNUSED_PAD src0_sel:DWORD src1_sel:WORD_0
	global_store_short v[26:27], v28, off
	s_branch .LBB0_360
